# context-row LayerNorm pass: K-slice partials summed four slices (16 loads) per trip instead of two, gate vector loads issued before the slice loop
# speedup vs baseline: 1.0055x; 1.0055x over previous
.LBB0_53:
	v_lshlrev_b32_e32 v0, 2, v22
	global_load_dwordx4 v[14:17], v0, s[10:11]
	global_load_dwordx4 v[10:13], v0, s[10:11] offset:1024
	global_load_dwordx4 v[2:5], v0, s[10:11] offset:2048
	global_load_dwordx4 v[6:9], v0, s[10:11] offset:3072
	s_andn2_b64 vcc, exec, s[8:9]
	s_cbranch_vccnz .LBB0_57
	s_mov_b32 s19, s27
	s_lshl_b64 s[8:9], s[18:19], 12
	v_mov_b32_e32 v18, 0
	v_lshl_add_u64 v[40:41], v[30:31], 0, s[8:9]
	s_mov_b32 s8, 0
	v_mov_b32_e32 v19, v18
	v_mov_b32_e32 v20, v18
	v_mov_b32_e32 v21, v18
	v_mov_b32_e32 v32, v18
	v_mov_b32_e32 v33, v18
	v_mov_b32_e32 v34, v18
	v_mov_b32_e32 v35, v18
	v_mov_b32_e32 v36, v18
	v_mov_b32_e32 v37, v18
	v_mov_b32_e32 v38, v18
	v_mov_b32_e32 v39, v18
	v_mov_b32_e32 v42, v18
	v_mov_b32_e32 v43, v18
	v_mov_b32_e32 v44, v18
	v_mov_b32_e32 v45, v18
	global_load_dwordx4 v[126:129], v[24:25], off
	global_load_dwordx4 v[130:133], v[24:25], off offset:1024
	global_load_dwordx4 v[134:137], v[24:25], off offset:2048
	global_load_dwordx4 v[138:141], v[24:25], off offset:3072
.Lsl4_loop:
	s_add_i32 s9, s8, 4
	s_cmp_le_u32 s9, s24
	s_cbranch_scc0 .Lsl4_tail
	s_mov_b32 s9, 0x200000
	v_add_co_u32_e32 v82, vcc, s9, v40
	s_nop 1
	v_addc_co_u32_e32 v83, vcc, 0, v41, vcc
	s_mov_b64 s[10:11], 0x400000
	v_lshl_add_u64 v[118:119], v[40:41], 0, s[10:11]
	v_lshl_add_u64 v[120:121], v[82:83], 0, s[10:11]
	global_load_dwordx4 v[54:57], v[40:41], off
	global_load_dwordx4 v[58:61], v[40:41], off offset:1024
	global_load_dwordx4 v[62:65], v[40:41], off offset:2048
	global_load_dwordx4 v[66:69], v[40:41], off offset:3072
	global_load_dwordx4 v[70:73], v[82:83], off
	global_load_dwordx4 v[74:77], v[82:83], off offset:1024
	global_load_dwordx4 v[78:81], v[82:83], off offset:2048
	global_load_dwordx4 v[122:125], v[82:83], off offset:3072
	global_load_dwordx4 v[86:89], v[118:119], off
	global_load_dwordx4 v[90:93], v[118:119], off offset:1024
	global_load_dwordx4 v[94:97], v[118:119], off offset:2048
	global_load_dwordx4 v[98:101], v[118:119], off offset:3072
	global_load_dwordx4 v[102:105], v[120:121], off
	global_load_dwordx4 v[106:109], v[120:121], off offset:1024
	global_load_dwordx4 v[110:113], v[120:121], off offset:2048
	global_load_dwordx4 v[114:117], v[120:121], off offset:3072
	s_mov_b64 s[10:11], 0x800000
	v_lshl_add_u64 v[40:41], v[40:41], 0, s[10:11]
	s_add_i32 s8, s8, 4
	s_waitcnt vmcnt(8)
	v_pk_add_f32 v[56:57], v[56:57], v[72:73]
	v_pk_add_f32 v[54:55], v[54:55], v[70:71]
	v_pk_add_f32 v[60:61], v[60:61], v[76:77]
	v_pk_add_f32 v[58:59], v[58:59], v[74:75]
	v_pk_add_f32 v[64:65], v[64:65], v[80:81]
	v_pk_add_f32 v[62:63], v[62:63], v[78:79]
	v_pk_add_f32 v[68:69], v[68:69], v[124:125]
	v_pk_add_f32 v[66:67], v[66:67], v[122:123]
	v_pk_add_f32 v[44:45], v[44:45], v[56:57]
	v_pk_add_f32 v[42:43], v[42:43], v[54:55]
	v_pk_add_f32 v[38:39], v[38:39], v[60:61]
	v_pk_add_f32 v[36:37], v[36:37], v[58:59]
	v_pk_add_f32 v[34:35], v[34:35], v[64:65]
	v_pk_add_f32 v[32:33], v[32:33], v[62:63]
	v_pk_add_f32 v[20:21], v[20:21], v[68:69]
	v_pk_add_f32 v[18:19], v[18:19], v[66:67]
	s_waitcnt vmcnt(0)
	v_pk_add_f32 v[88:89], v[88:89], v[104:105]
	v_pk_add_f32 v[86:87], v[86:87], v[102:103]
	v_pk_add_f32 v[92:93], v[92:93], v[108:109]
	v_pk_add_f32 v[90:91], v[90:91], v[106:107]
	v_pk_add_f32 v[96:97], v[96:97], v[112:113]
	v_pk_add_f32 v[94:95], v[94:95], v[110:111]
	v_pk_add_f32 v[100:101], v[100:101], v[116:117]
	v_pk_add_f32 v[98:99], v[98:99], v[114:115]
	v_pk_add_f32 v[44:45], v[44:45], v[88:89]
	v_pk_add_f32 v[42:43], v[42:43], v[86:87]
	v_pk_add_f32 v[38:39], v[38:39], v[92:93]
	v_pk_add_f32 v[36:37], v[36:37], v[90:91]
	v_pk_add_f32 v[34:35], v[34:35], v[96:97]
	v_pk_add_f32 v[32:33], v[32:33], v[94:95]
	v_pk_add_f32 v[20:21], v[20:21], v[100:101]
	v_pk_add_f32 v[18:19], v[18:19], v[98:99]
	s_branch .Lsl4_loop
.Lsl4_tail:
	s_cmp_lt_u32 s8, s24
	s_cbranch_scc0 .Lsl4_done

.Lsl4_done:
	v_mov_b64_e32 v[54:55], v[126:127]
	v_mov_b64_e32 v[56:57], v[128:129]
	s_mov_b32 s8, 0x3fb504f3
	s_waitcnt vmcnt(0)
	v_pk_mul_f32 v[40:41], v[56:57], v[44:45]
	v_pk_mul_f32 v[42:43], v[54:55], v[42:43]
	v_pk_fma_f32 v[16:17], v[16:17], s[8:9], v[40:41] op_sel_hi:[1,0,1]
	v_pk_fma_f32 v[14:15], v[14:15], s[8:9], v[42:43] op_sel_hi:[1,0,1]
	v_mov_b64_e32 v[40:41], v[130:131]
	v_mov_b64_e32 v[42:43], v[132:133]
	s_waitcnt vmcnt(0)
	v_pk_mul_f32 v[38:39], v[42:43], v[38:39]
	v_pk_mul_f32 v[36:37], v[40:41], v[36:37]
	v_pk_fma_f32 v[12:13], v[12:13], s[8:9], v[38:39] op_sel_hi:[1,0,1]
	v_pk_fma_f32 v[10:11], v[10:11], s[8:9], v[36:37] op_sel_hi:[1,0,1]
	v_mov_b64_e32 v[36:37], v[134:135]
	v_mov_b64_e32 v[38:39], v[136:137]
	s_waitcnt vmcnt(0)
	v_pk_mul_f32 v[34:35], v[38:39], v[34:35]
	v_pk_mul_f32 v[32:33], v[36:37], v[32:33]
	v_pk_fma_f32 v[4:5], v[4:5], s[8:9], v[34:35] op_sel_hi:[1,0,1]
	v_pk_fma_f32 v[2:3], v[2:3], s[8:9], v[32:33] op_sel_hi:[1,0,1]
	v_mov_b64_e32 v[32:33], v[138:139]
	v_mov_b64_e32 v[34:35], v[140:141]
	s_waitcnt vmcnt(0)
	v_pk_mul_f32 v[18:19], v[32:33], v[18:19]
	v_pk_mul_f32 v[20:21], v[34:35], v[20:21]
	v_pk_fma_f32 v[18:19], v[6:7], s[8:9], v[18:19] op_sel_hi:[1,0,1]
	v_pk_fma_f32 v[20:21], v[8:9], s[8:9], v[20:21] op_sel_hi:[1,0,1]
	v_mov_b32_e32 v39, v18
	v_mov_b64_e32 v[6:7], v[18:19]
	v_mov_b32_e32 v37, v20
	v_mov_b32_e32 v32, v11
	v_mov_b32_e32 v35, v16
	v_mov_b32_e32 v34, v15
	v_mov_b32_e32 v16, v14
	v_mov_b64_e32 v[8:9], v[20:21]
	s_branch .LBB0_58
